# cache-policy lever: nt (non-temporal) hint on the MLP1 GEMM epilogue stores (write-once 335 MB intermediate), otherwise identical to the previous version
# speedup vs baseline: 1.0155x; 1.0014x over previous
; __device__ __forceinline__ unsigned pk2(float lo, float hi) { const v2f_t f = {lo, hi}; const v2bf_t b = __builtin_convertvector(f, v2bf_t); return __builtin_bit_cast(unsigned, b); }
;     __device__ __forceinline__ void operator()(const f32x4 (&acc)[2][2][4][2], const Unit& u, int wr, int wc, int fr, int fq) const {
;         const int row0 = u.pm * 256 + wr * 64 + fr, col0 = u.pn * 256 + wc * 32 + 8 * fq;
;         f32x4 bv[2][2];
; #pragma unroll
;         for (int bj = 0; bj < 2; ++bj)
; #pragma unroll
;             for (int n = 0; n < 2; ++n) bv[bj][n] = *(const f32x4*)(bias + col0 + bj * 128 + 4 * n);
; #pragma unroll
;         for (int ai = 0; ai < 2; ++ai)
; #pragma unroll
;             for (int m = 0; m < 4; ++m) { bf16_t* rowp = a1 + (size_t)(row0 + ai * 128 + m * 16) * DFF + col0;
; #pragma unroll
;                 for (int bj = 0; bj < 2; ++bj) { f32x4 v0 = acc[ai][bj][m][0] + bv[bj][0], v1 = acc[ai][bj][m][1] + bv[bj][1];
; #pragma unroll
;                     for (int j = 0; j < 4; ++j) { const float a = fmaxf(v0[j], 0.f), b = fmaxf(v1[j], 0.f); v0[j] = a * a; v1[j] = b * b; }
;                     u32x4 w; w.x = pk2(v0[0], v0[1]); w.y = pk2(v0[2], v0[3]); w.z = pk2(v1[0], v1[1]); w.w = pk2(v1[2], v1[3]);
;                     *(u32x4*)(rowp + bj * 128) = w; } }
.LBB0_851:
	v_bfe_u32 v156, v194, 8, 1
	v_lshlrev_b32_e32 v156, 4, v156
	v_and_b32_e32 v157, 15, v194
	v_add_u32_e32 v156, v156, v157
	v_mul_u32_u24_e32 v186, 0x110, v156
	v_bfe_u32 v158, v194, 6, 2
	v_bfe_u32 v159, v194, 4, 2
	v_lshl_add_u32 v186, v158, 6, v186
	v_lshl_add_u32 v186, v159, 4, v186
	v_add_u32_e32 v186, 0x23410, v186
	v_lshrrev_b32_e32 v160, 6, v194
	v_lshl_add_u32 v160, v160, 2, v159
	v_mul_u32_u24_e32 v187, 0x110, v160
	v_lshl_add_u32 v187, v157, 4, v187
	v_add_u32_e32 v187, 0x23410, v187
	v_bfe_u32 v156, v194, 8, 1
	v_lshlrev_b32_e32 v156, 6, v156
	v_lshl_add_u32 v156, v158, 2, v156
	v_add_u32_e32 v156, v156, v159
	v_lshl_add_u32 v160, s30, 8, v156
	v_mov_b32_e32 v161, 0
	v_lshlrev_b64 v[160:161], 14, v[160:161]
	v_lshlrev_b32_e32 v158, 4, v157
	v_lshl_add_u32 v158, s34, 9, v158
	v_mov_b32_e32 v159, 0
	v_lshl_add_u64 v[188:189], s[14:15], 0, v[160:161]
	v_lshl_add_u64 v[188:189], v[188:189], 0, v[158:159]
	s_mov_b32 s21, 0x200000
	s_mov_b64 s[36:37], 0x200000
	s_mov_b32 s62, s61
	s_mov_b32 s34, s20
	s_mov_b32 s30, s22
	s_mov_b64 s[38:39], s[28:29]
	s_mov_b32 s99, 0
	s_waitcnt vmcnt(6)
	v_pk_add_f32 v[142:143], v[142:143], v[240:241]
	v_pk_add_f32 v[144:145], v[144:145], v[242:243]
	v_max_f32_e32 v142, 0, v142
	v_max_f32_e32 v143, 0, v143
	v_max_f32_e32 v144, 0, v144
	v_max_f32_e32 v145, 0, v145
	v_pk_mul_f32 v[142:143], v[142:143], v[142:143]
	v_pk_mul_f32 v[144:145], v[144:145], v[144:145]
	v_pk_add_f32 v[138:139], v[138:139], v[244:245]
	v_pk_add_f32 v[140:141], v[140:141], v[246:247]
	v_max_f32_e32 v138, 0, v138
	v_max_f32_e32 v139, 0, v139
	v_max_f32_e32 v140, 0, v140
	v_max_f32_e32 v141, 0, v141
	v_pk_mul_f32 v[138:139], v[138:139], v[138:139]
	v_pk_mul_f32 v[140:141], v[140:141], v[140:141]
	v_cvt_pk_bf16_f32 v174, v142, v143
	v_cvt_pk_bf16_f32 v175, v144, v145
	v_cvt_pk_bf16_f32 v176, v138, v139
	v_cvt_pk_bf16_f32 v177, v140, v141
	ds_write_b128 v186, v[174:177]
	s_waitcnt lgkmcnt(0)
	s_barrier
	ds_read_b128 v[178:181], v187
	s_mov_b32 s98, 0x0
	v_lshl_add_u64 v[190:191], v[188:189], 0, s[98:99]
	v_pk_add_f32 v[134:135], v[134:135], v[248:249]
	v_pk_add_f32 v[136:137], v[136:137], v[250:251]
	v_max_f32_e32 v134, 0, v134
	v_max_f32_e32 v135, 0, v135
	v_max_f32_e32 v136, 0, v136
	v_max_f32_e32 v137, 0, v137
	v_pk_mul_f32 v[134:135], v[134:135], v[134:135]
	v_pk_mul_f32 v[136:137], v[136:137], v[136:137]
	v_pk_add_f32 v[130:131], v[130:131], v[252:253]
	v_pk_add_f32 v[132:133], v[132:133], v[254:255]
	v_max_f32_e32 v130, 0, v130
	v_max_f32_e32 v131, 0, v131
	v_max_f32_e32 v132, 0, v132
	v_max_f32_e32 v133, 0, v133
	v_pk_mul_f32 v[130:131], v[130:131], v[130:131]
	v_pk_mul_f32 v[132:133], v[132:133], v[132:133]
	v_cvt_pk_bf16_f32 v174, v134, v135
	v_cvt_pk_bf16_f32 v175, v136, v137
	v_cvt_pk_bf16_f32 v176, v130, v131
	v_cvt_pk_bf16_f32 v177, v132, v133
	ds_write_b128 v186, v[174:177] offset:8704
	s_waitcnt lgkmcnt(1)
	global_store_dwordx4 v[190:191], v[178:181], off nt
	s_waitcnt lgkmcnt(0)
	s_barrier
	ds_read_b128 v[182:185], v187 offset:8704
	v_pk_add_f32 v[110:111], v[110:111], v[240:241]
	v_pk_add_f32 v[112:113], v[112:113], v[242:243]
	v_max_f32_e32 v110, 0, v110
	v_max_f32_e32 v111, 0, v111
	v_max_f32_e32 v112, 0, v112
	v_max_f32_e32 v113, 0, v113
	v_pk_mul_f32 v[110:111], v[110:111], v[110:111]
	v_pk_mul_f32 v[112:113], v[112:113], v[112:113]
	v_pk_add_f32 v[106:107], v[106:107], v[244:245]
	v_pk_add_f32 v[108:109], v[108:109], v[246:247]
	v_max_f32_e32 v106, 0, v106
	v_max_f32_e32 v107, 0, v107
	v_max_f32_e32 v108, 0, v108
	v_max_f32_e32 v109, 0, v109
	v_pk_mul_f32 v[106:107], v[106:107], v[106:107]
	v_pk_mul_f32 v[108:109], v[108:109], v[108:109]
	v_cvt_pk_bf16_f32 v174, v110, v111
	v_cvt_pk_bf16_f32 v175, v112, v113
	v_cvt_pk_bf16_f32 v176, v106, v107
	v_cvt_pk_bf16_f32 v177, v108, v109
	ds_write_b128 v186, v[174:177]
	s_waitcnt lgkmcnt(1)
	global_store_dwordx4 v[190:191], v[182:185], off offset:256 nt
	s_waitcnt lgkmcnt(0)
	s_barrier
	ds_read_b128 v[178:181], v187
	s_mov_b32 s98, 0x40000
	v_lshl_add_u64 v[190:191], v[188:189], 0, s[98:99]
	v_pk_add_f32 v[102:103], v[102:103], v[248:249]
	v_pk_add_f32 v[104:105], v[104:105], v[250:251]
	v_max_f32_e32 v102, 0, v102
	v_max_f32_e32 v103, 0, v103
	v_max_f32_e32 v104, 0, v104
	v_max_f32_e32 v105, 0, v105
	v_pk_mul_f32 v[102:103], v[102:103], v[102:103]
	v_pk_mul_f32 v[104:105], v[104:105], v[104:105]
	v_pk_add_f32 v[98:99], v[98:99], v[252:253]
	v_pk_add_f32 v[100:101], v[100:101], v[254:255]
	v_max_f32_e32 v98, 0, v98
	v_max_f32_e32 v99, 0, v99
	v_max_f32_e32 v100, 0, v100
	v_max_f32_e32 v101, 0, v101
	v_pk_mul_f32 v[98:99], v[98:99], v[98:99]
	v_pk_mul_f32 v[100:101], v[100:101], v[100:101]
	v_cvt_pk_bf16_f32 v174, v102, v103
	v_cvt_pk_bf16_f32 v175, v104, v105
	v_cvt_pk_bf16_f32 v176, v98, v99
	v_cvt_pk_bf16_f32 v177, v100, v101
	ds_write_b128 v186, v[174:177] offset:8704
	s_waitcnt lgkmcnt(1)
	global_store_dwordx4 v[190:191], v[178:181], off nt
	s_waitcnt lgkmcnt(0)
	s_barrier
	ds_read_b128 v[182:185], v187 offset:8704
	v_pk_add_f32 v[94:95], v[94:95], v[240:241]
	v_pk_add_f32 v[96:97], v[96:97], v[242:243]
	v_max_f32_e32 v94, 0, v94
	v_max_f32_e32 v95, 0, v95
	v_max_f32_e32 v96, 0, v96
	v_max_f32_e32 v97, 0, v97
	v_pk_mul_f32 v[94:95], v[94:95], v[94:95]
	v_pk_mul_f32 v[96:97], v[96:97], v[96:97]
	v_pk_add_f32 v[90:91], v[90:91], v[244:245]
	v_pk_add_f32 v[92:93], v[92:93], v[246:247]
	v_max_f32_e32 v90, 0, v90
	v_max_f32_e32 v91, 0, v91
	v_max_f32_e32 v92, 0, v92
	v_max_f32_e32 v93, 0, v93
	v_pk_mul_f32 v[90:91], v[90:91], v[90:91]
	v_pk_mul_f32 v[92:93], v[92:93], v[92:93]
	v_cvt_pk_bf16_f32 v174, v94, v95
	v_cvt_pk_bf16_f32 v175, v96, v97
	v_cvt_pk_bf16_f32 v176, v90, v91
	v_cvt_pk_bf16_f32 v177, v92, v93
	ds_write_b128 v186, v[174:177]
	s_waitcnt lgkmcnt(1)
	global_store_dwordx4 v[190:191], v[182:185], off offset:256 nt
	s_waitcnt lgkmcnt(0)
	s_barrier
; __device__ __forceinline__ unsigned pk2(float lo, float hi) { const v2f_t f = {lo, hi}; const v2bf_t b = __builtin_convertvector(f, v2bf_t); return __builtin_bit_cast(unsigned, b); }
;     __device__ __forceinline__ void operator()(const f32x4 (&acc)[2][2][4][2], const Unit& u, int wr, int wc, int fr, int fq) const {
;     ...
;         for (int ai = 0; ai < 2; ++ai)
; #pragma unroll
;             for (int m = 0; m < 4; ++m) { bf16_t* rowp = a1 + (size_t)(row0 + ai * 128 + m * 16) * DFF + col0;
; #pragma unroll
;                 for (int bj = 0; bj < 2; ++bj) { f32x4 v0 = acc[ai][bj][m][0] + bv[bj][0], v1 = acc[ai][bj][m][1] + bv[bj][1];
; #pragma unroll
;                     for (int j = 0; j < 4; ++j) { const float a = fmaxf(v0[j], 0.f), b = fmaxf(v1[j], 0.f); v0[j] = a * a; v1[j] = b * b; }
;                     u32x4 w; w.x = pk2(v0[0], v0[1]); w.y = pk2(v0[2], v0[3]); w.z = pk2(v1[0], v1[1]); w.w = pk2(v1[2], v1[3]);
;                     *(u32x4*)(rowp + bj * 128) = w; } }
	ds_read_b128 v[178:181], v187
	s_mov_b32 s98, 0x80000
	v_lshl_add_u64 v[190:191], v[188:189], 0, s[98:99]
	v_pk_add_f32 v[86:87], v[86:87], v[248:249]
	v_pk_add_f32 v[88:89], v[88:89], v[250:251]
	v_max_f32_e32 v86, 0, v86
	v_max_f32_e32 v87, 0, v87
	v_max_f32_e32 v88, 0, v88
	v_max_f32_e32 v89, 0, v89
	v_pk_mul_f32 v[86:87], v[86:87], v[86:87]
	v_pk_mul_f32 v[88:89], v[88:89], v[88:89]
	v_pk_add_f32 v[82:83], v[82:83], v[252:253]
	v_pk_add_f32 v[84:85], v[84:85], v[254:255]
	v_max_f32_e32 v82, 0, v82
	v_max_f32_e32 v83, 0, v83
	v_max_f32_e32 v84, 0, v84
	v_max_f32_e32 v85, 0, v85
	v_pk_mul_f32 v[82:83], v[82:83], v[82:83]
	v_pk_mul_f32 v[84:85], v[84:85], v[84:85]
	v_cvt_pk_bf16_f32 v174, v86, v87
	v_cvt_pk_bf16_f32 v175, v88, v89
	v_cvt_pk_bf16_f32 v176, v82, v83
	v_cvt_pk_bf16_f32 v177, v84, v85
	ds_write_b128 v186, v[174:177] offset:8704
	s_waitcnt lgkmcnt(1)
	global_store_dwordx4 v[190:191], v[178:181], off nt
	s_waitcnt lgkmcnt(0)
	s_barrier
	ds_read_b128 v[182:185], v187 offset:8704
	v_pk_add_f32 v[78:79], v[78:79], v[240:241]
	v_pk_add_f32 v[80:81], v[80:81], v[242:243]
	v_max_f32_e32 v78, 0, v78
	v_max_f32_e32 v79, 0, v79
	v_max_f32_e32 v80, 0, v80
	v_max_f32_e32 v81, 0, v81
	v_pk_mul_f32 v[78:79], v[78:79], v[78:79]
	v_pk_mul_f32 v[80:81], v[80:81], v[80:81]
	v_pk_add_f32 v[74:75], v[74:75], v[244:245]
	v_pk_add_f32 v[76:77], v[76:77], v[246:247]
	v_max_f32_e32 v74, 0, v74
	v_max_f32_e32 v75, 0, v75
	v_max_f32_e32 v76, 0, v76
	v_max_f32_e32 v77, 0, v77
	v_pk_mul_f32 v[74:75], v[74:75], v[74:75]
	v_pk_mul_f32 v[76:77], v[76:77], v[76:77]
	v_cvt_pk_bf16_f32 v174, v78, v79
	v_cvt_pk_bf16_f32 v175, v80, v81
	v_cvt_pk_bf16_f32 v176, v74, v75
	v_cvt_pk_bf16_f32 v177, v76, v77
	ds_write_b128 v186, v[174:177]
	s_waitcnt lgkmcnt(1)
	global_store_dwordx4 v[190:191], v[182:185], off offset:256 nt
	s_waitcnt lgkmcnt(0)
	s_barrier
	ds_read_b128 v[178:181], v187
	s_mov_b32 s98, 0xc0000
	v_lshl_add_u64 v[190:191], v[188:189], 0, s[98:99]
	v_pk_add_f32 v[70:71], v[70:71], v[248:249]
	v_pk_add_f32 v[72:73], v[72:73], v[250:251]
	v_max_f32_e32 v70, 0, v70
	v_max_f32_e32 v71, 0, v71
	v_max_f32_e32 v72, 0, v72
	v_max_f32_e32 v73, 0, v73
	v_pk_mul_f32 v[70:71], v[70:71], v[70:71]
	v_pk_mul_f32 v[72:73], v[72:73], v[72:73]
	v_pk_add_f32 v[66:67], v[66:67], v[252:253]
	v_pk_add_f32 v[68:69], v[68:69], v[254:255]
	v_max_f32_e32 v66, 0, v66
	v_max_f32_e32 v67, 0, v67
	v_max_f32_e32 v68, 0, v68
	v_max_f32_e32 v69, 0, v69
	v_pk_mul_f32 v[66:67], v[66:67], v[66:67]
	v_pk_mul_f32 v[68:69], v[68:69], v[68:69]
	v_cvt_pk_bf16_f32 v174, v70, v71
	v_cvt_pk_bf16_f32 v175, v72, v73
	v_cvt_pk_bf16_f32 v176, v66, v67
	v_cvt_pk_bf16_f32 v177, v68, v69
	ds_write_b128 v186, v[174:177] offset:8704
	s_waitcnt lgkmcnt(1)
	global_store_dwordx4 v[190:191], v[178:181], off nt
	s_waitcnt lgkmcnt(0)
	s_barrier
	ds_read_b128 v[182:185], v187 offset:8704
	v_pk_add_f32 v[60:61], v[60:61], v[240:241]
	v_pk_add_f32 v[62:63], v[62:63], v[242:243]
	v_max_f32_e32 v60, 0, v60
	v_max_f32_e32 v61, 0, v61
	v_max_f32_e32 v62, 0, v62
	v_max_f32_e32 v63, 0, v63
	v_pk_mul_f32 v[60:61], v[60:61], v[60:61]
	v_pk_mul_f32 v[62:63], v[62:63], v[62:63]
	v_pk_add_f32 v[56:57], v[56:57], v[244:245]
	v_pk_add_f32 v[58:59], v[58:59], v[246:247]
	v_max_f32_e32 v56, 0, v56
	v_max_f32_e32 v57, 0, v57
	v_max_f32_e32 v58, 0, v58
	v_max_f32_e32 v59, 0, v59
	v_pk_mul_f32 v[56:57], v[56:57], v[56:57]
	v_pk_mul_f32 v[58:59], v[58:59], v[58:59]
	v_cvt_pk_bf16_f32 v174, v60, v61
	v_cvt_pk_bf16_f32 v175, v62, v63
	v_cvt_pk_bf16_f32 v176, v56, v57
	v_cvt_pk_bf16_f32 v177, v58, v59
	ds_write_b128 v186, v[174:177]
	s_waitcnt lgkmcnt(1)
	global_store_dwordx4 v[190:191], v[182:185], off offset:256 nt
	s_waitcnt lgkmcnt(0)
	s_barrier
	ds_read_b128 v[178:181], v187
	s_mov_b32 s98, 0x200000
	v_lshl_add_u64 v[190:191], v[188:189], 0, s[98:99]
	v_pk_add_f32 v[52:53], v[52:53], v[248:249]
	v_pk_add_f32 v[54:55], v[54:55], v[250:251]
	v_max_f32_e32 v52, 0, v52
	v_max_f32_e32 v53, 0, v53
	v_max_f32_e32 v54, 0, v54
	v_max_f32_e32 v55, 0, v55
	v_pk_mul_f32 v[52:53], v[52:53], v[52:53]
	v_pk_mul_f32 v[54:55], v[54:55], v[54:55]
	v_pk_add_f32 v[48:49], v[48:49], v[252:253]
	v_pk_add_f32 v[50:51], v[50:51], v[254:255]
	v_max_f32_e32 v48, 0, v48
	v_max_f32_e32 v49, 0, v49
	v_max_f32_e32 v50, 0, v50
	v_max_f32_e32 v51, 0, v51
	v_pk_mul_f32 v[48:49], v[48:49], v[48:49]
	v_pk_mul_f32 v[50:51], v[50:51], v[50:51]
	v_cvt_pk_bf16_f32 v174, v52, v53
	v_cvt_pk_bf16_f32 v175, v54, v55
	v_cvt_pk_bf16_f32 v176, v48, v49
	v_cvt_pk_bf16_f32 v177, v50, v51
	ds_write_b128 v186, v[174:177] offset:8704
	s_waitcnt lgkmcnt(1)
	global_store_dwordx4 v[190:191], v[178:181], off nt
	s_waitcnt lgkmcnt(0)
	s_barrier
	ds_read_b128 v[182:185], v187 offset:8704
	v_pk_add_f32 v[44:45], v[44:45], v[240:241]
	v_pk_add_f32 v[46:47], v[46:47], v[242:243]
	v_max_f32_e32 v44, 0, v44
	v_max_f32_e32 v45, 0, v45
	v_max_f32_e32 v46, 0, v46
	v_max_f32_e32 v47, 0, v47
	v_pk_mul_f32 v[44:45], v[44:45], v[44:45]
	v_pk_mul_f32 v[46:47], v[46:47], v[46:47]
	v_pk_add_f32 v[40:41], v[40:41], v[244:245]
	v_pk_add_f32 v[42:43], v[42:43], v[246:247]
	v_max_f32_e32 v40, 0, v40
	v_max_f32_e32 v41, 0, v41
	v_max_f32_e32 v42, 0, v42
	v_max_f32_e32 v43, 0, v43
	v_pk_mul_f32 v[40:41], v[40:41], v[40:41]
	v_pk_mul_f32 v[42:43], v[42:43], v[42:43]
	v_cvt_pk_bf16_f32 v174, v44, v45
	v_cvt_pk_bf16_f32 v175, v46, v47
	v_cvt_pk_bf16_f32 v176, v40, v41
	v_cvt_pk_bf16_f32 v177, v42, v43
	ds_write_b128 v186, v[174:177]
	s_waitcnt lgkmcnt(1)
	global_store_dwordx4 v[190:191], v[182:185], off offset:256 nt
	s_waitcnt lgkmcnt(0)
	s_barrier
; __device__ __forceinline__ unsigned pk2(float lo, float hi) { const v2f_t f = {lo, hi}; const v2bf_t b = __builtin_convertvector(f, v2bf_t); return __builtin_bit_cast(unsigned, b); }
;     __device__ __forceinline__ void operator()(const f32x4 (&acc)[2][2][4][2], const Unit& u, int wr, int wc, int fr, int fq) const {
;     ...
;         for (int ai = 0; ai < 2; ++ai)
; #pragma unroll
;             for (int m = 0; m < 4; ++m) { bf16_t* rowp = a1 + (size_t)(row0 + ai * 128 + m * 16) * DFF + col0;
; #pragma unroll
;                 for (int bj = 0; bj < 2; ++bj) { f32x4 v0 = acc[ai][bj][m][0] + bv[bj][0], v1 = acc[ai][bj][m][1] + bv[bj][1];
; #pragma unroll
;                     for (int j = 0; j < 4; ++j) { const float a = fmaxf(v0[j], 0.f), b = fmaxf(v1[j], 0.f); v0[j] = a * a; v1[j] = b * b; }
;                     u32x4 w; w.x = pk2(v0[0], v0[1]); w.y = pk2(v0[2], v0[3]); w.z = pk2(v1[0], v1[1]); w.w = pk2(v1[2], v1[3]);
;                     *(u32x4*)(rowp + bj * 128) = w; } }
	ds_read_b128 v[178:181], v187
	s_mov_b32 s98, 0x240000
	v_lshl_add_u64 v[190:191], v[188:189], 0, s[98:99]
	v_pk_add_f32 v[36:37], v[36:37], v[248:249]
	v_pk_add_f32 v[38:39], v[38:39], v[250:251]
	v_max_f32_e32 v36, 0, v36
	v_max_f32_e32 v37, 0, v37
	v_max_f32_e32 v38, 0, v38
	v_max_f32_e32 v39, 0, v39
	v_pk_mul_f32 v[36:37], v[36:37], v[36:37]
	v_pk_mul_f32 v[38:39], v[38:39], v[38:39]
	v_pk_add_f32 v[32:33], v[32:33], v[252:253]
	v_pk_add_f32 v[34:35], v[34:35], v[254:255]
	v_max_f32_e32 v32, 0, v32
	v_max_f32_e32 v33, 0, v33
	v_max_f32_e32 v34, 0, v34
	v_max_f32_e32 v35, 0, v35
	v_pk_mul_f32 v[32:33], v[32:33], v[32:33]
	v_pk_mul_f32 v[34:35], v[34:35], v[34:35]
	v_cvt_pk_bf16_f32 v174, v36, v37
	v_cvt_pk_bf16_f32 v175, v38, v39
	v_cvt_pk_bf16_f32 v176, v32, v33
	v_cvt_pk_bf16_f32 v177, v34, v35
	ds_write_b128 v186, v[174:177] offset:8704
	s_waitcnt lgkmcnt(1)
	global_store_dwordx4 v[190:191], v[178:181], off nt
	s_waitcnt lgkmcnt(0)
	s_barrier
	ds_read_b128 v[182:185], v187 offset:8704
	v_pk_add_f32 v[28:29], v[28:29], v[240:241]
	v_pk_add_f32 v[30:31], v[30:31], v[242:243]
	v_max_f32_e32 v28, 0, v28
	v_max_f32_e32 v29, 0, v29
	v_max_f32_e32 v30, 0, v30
	v_max_f32_e32 v31, 0, v31
	v_pk_mul_f32 v[28:29], v[28:29], v[28:29]
	v_pk_mul_f32 v[30:31], v[30:31], v[30:31]
	v_pk_add_f32 v[24:25], v[24:25], v[244:245]
	v_pk_add_f32 v[26:27], v[26:27], v[246:247]
	v_max_f32_e32 v24, 0, v24
	v_max_f32_e32 v25, 0, v25
	v_max_f32_e32 v26, 0, v26
	v_max_f32_e32 v27, 0, v27
	v_pk_mul_f32 v[24:25], v[24:25], v[24:25]
	v_pk_mul_f32 v[26:27], v[26:27], v[26:27]
	v_cvt_pk_bf16_f32 v174, v28, v29
	v_cvt_pk_bf16_f32 v175, v30, v31
	v_cvt_pk_bf16_f32 v176, v24, v25
	v_cvt_pk_bf16_f32 v177, v26, v27
	ds_write_b128 v186, v[174:177]
	s_waitcnt lgkmcnt(1)
	global_store_dwordx4 v[190:191], v[182:185], off offset:256 nt
	s_waitcnt lgkmcnt(0)
	s_barrier
	ds_read_b128 v[178:181], v187
	s_mov_b32 s98, 0x280000
	v_lshl_add_u64 v[190:191], v[188:189], 0, s[98:99]
	v_pk_add_f32 v[20:21], v[20:21], v[248:249]
	v_pk_add_f32 v[22:23], v[22:23], v[250:251]
	v_max_f32_e32 v20, 0, v20
	v_max_f32_e32 v21, 0, v21
	v_max_f32_e32 v22, 0, v22
	v_max_f32_e32 v23, 0, v23
	v_pk_mul_f32 v[20:21], v[20:21], v[20:21]
	v_pk_mul_f32 v[22:23], v[22:23], v[22:23]
	v_pk_add_f32 v[16:17], v[16:17], v[252:253]
	v_pk_add_f32 v[18:19], v[18:19], v[254:255]
	v_max_f32_e32 v16, 0, v16
	v_max_f32_e32 v17, 0, v17
	v_max_f32_e32 v18, 0, v18
	v_max_f32_e32 v19, 0, v19
	v_pk_mul_f32 v[16:17], v[16:17], v[16:17]
	v_pk_mul_f32 v[18:19], v[18:19], v[18:19]
	v_cvt_pk_bf16_f32 v174, v20, v21
	v_cvt_pk_bf16_f32 v175, v22, v23
	v_cvt_pk_bf16_f32 v176, v16, v17
	v_cvt_pk_bf16_f32 v177, v18, v19
	ds_write_b128 v186, v[174:177] offset:8704
	s_waitcnt lgkmcnt(1)
	global_store_dwordx4 v[190:191], v[178:181], off nt
	s_waitcnt lgkmcnt(0)
	s_barrier
	ds_read_b128 v[182:185], v187 offset:8704
	v_pk_add_f32 v[12:13], v[12:13], v[240:241]
	v_pk_add_f32 v[14:15], v[14:15], v[242:243]
	v_max_f32_e32 v12, 0, v12
	v_max_f32_e32 v13, 0, v13
	v_max_f32_e32 v14, 0, v14
	v_max_f32_e32 v15, 0, v15
	v_pk_mul_f32 v[12:13], v[12:13], v[12:13]
	v_pk_mul_f32 v[14:15], v[14:15], v[14:15]
	v_pk_add_f32 v[8:9], v[8:9], v[244:245]
	v_pk_add_f32 v[10:11], v[10:11], v[246:247]
	v_max_f32_e32 v8, 0, v8
	v_max_f32_e32 v9, 0, v9
	v_max_f32_e32 v10, 0, v10
	v_max_f32_e32 v11, 0, v11
	v_pk_mul_f32 v[8:9], v[8:9], v[8:9]
	v_pk_mul_f32 v[10:11], v[10:11], v[10:11]
	v_cvt_pk_bf16_f32 v174, v12, v13
	v_cvt_pk_bf16_f32 v175, v14, v15
	v_cvt_pk_bf16_f32 v176, v8, v9
	v_cvt_pk_bf16_f32 v177, v10, v11
	ds_write_b128 v186, v[174:177]
	s_waitcnt lgkmcnt(1)
	global_store_dwordx4 v[190:191], v[182:185], off offset:256 nt
	s_waitcnt lgkmcnt(0)
	s_barrier
	ds_read_b128 v[178:181], v187
	s_mov_b32 s98, 0x2c0000
	v_lshl_add_u64 v[190:191], v[188:189], 0, s[98:99]
	v_pk_add_f32 v[4:5], v[4:5], v[248:249]
	v_pk_add_f32 v[6:7], v[6:7], v[250:251]
	v_max_f32_e32 v4, 0, v4
	v_max_f32_e32 v5, 0, v5
	v_max_f32_e32 v6, 0, v6
	v_max_f32_e32 v7, 0, v7
	v_pk_mul_f32 v[4:5], v[4:5], v[4:5]
	v_pk_mul_f32 v[6:7], v[6:7], v[6:7]
	v_pk_add_f32 v[0:1], v[0:1], v[252:253]
	v_pk_add_f32 v[2:3], v[2:3], v[254:255]
	v_max_f32_e32 v0, 0, v0
	v_max_f32_e32 v1, 0, v1
	v_max_f32_e32 v2, 0, v2
	v_max_f32_e32 v3, 0, v3
	v_pk_mul_f32 v[0:1], v[0:1], v[0:1]
	v_pk_mul_f32 v[2:3], v[2:3], v[2:3]
	v_cvt_pk_bf16_f32 v174, v4, v5
	v_cvt_pk_bf16_f32 v175, v6, v7
	v_cvt_pk_bf16_f32 v176, v0, v1
	v_cvt_pk_bf16_f32 v177, v2, v3
	ds_write_b128 v186, v[174:177] offset:8704
	s_waitcnt lgkmcnt(1)
	global_store_dwordx4 v[190:191], v[178:181], off nt
	s_waitcnt lgkmcnt(0)
	s_barrier
	ds_read_b128 v[182:185], v187 offset:8704
	s_waitcnt lgkmcnt(0)
	global_store_dwordx4 v[190:191], v[182:185], off offset:256 nt
	s_and_b64 vcc, exec, s[26:27]
	s_mov_b64 s[36:37], s[24:25]
	s_cbranch_vccnz .LBB0_861
